# MLA back edge: exit test and two address adds rotated ahead of the leading half's loop-back barrier (7.11), trailing half's branch target kept on a 32-byte line start
# baseline (speedup 1.0000x reference)
; __device__ __forceinline__ unsigned cvt_pk_bf16(float lo, float hi) { unsigned r; asm volatile("v_cvt_pk_bf16_f32 %0, %1, %2" : "=v"(r) : "v"(lo), "v"(hi)); return r; }
; #define SLOAD(j) do { const size_t krow = (size_t)(seq0 + key0 + 64 * (j) + sr); kst = *(const bf16x8*)(Kp + krow * ldk + sc); vstg = *(const bf16x8*)(Vp + krow * ldk + sc); \
;         if (MODE == 2) { if (tid < 256) pst = *(const bf16x8*)(Kpe + (size_t)(seq0 + key0 + 64 * (j) + pr) * 32 + pc); } } while (0)
; #define SWRITE(b) do { *(bf16x8*)(lds + A_K0 + (b) * A_KBUF + sr * KSTR + sc * 2) = kst; *(bf16x8*)(lds + A_V0 + (b) * A_VBUF + vst) = vstg; \
;         if (MODE == 2) { if (tid < 256) *(bf16x8*)(lds + A_K0 + (b) * A_KBUF + pr * KSTR + 128 + pc * 2) = pst; } } while (0)
; #define SLOAD(S, j) do { const size_t krow = (size_t)(seq0 + 64 * (j) + sr); ks##S = *(const bf16x8*)(Kp + krow * 1024 + sc); vs##S = *(const bf16x8*)(Vp + krow * 1024 + sc); \
;         ps##S = *(const bf16x8*)(Kpe + (size_t)(seq0 + 64 * (j) + pr) * 32 + pc); } while (0)
; __device__ __forceinline__ bf16x8 pack8(const f32x16& p, int base) {
;     u32x4 w = {cvt_pk_bf16(p[base + 0], p[base + 1]), cvt_pk_bf16(p[base + 2], p[base + 3]), cvt_pk_bf16(p[base + 4], p[base + 5]), cvt_pk_bf16(p[base + 6], p[base + 7])};
;     return *reinterpret_cast<bf16x8*>(&w);
; }
; __device__ __forceinline__ void mla_unit2(const Params& P, unsigned char* lds, int h, int rb, int grp, bool dry = false) {
;     ...
;     for (int i = 0; i < NT; i += 2) {
;         SLOAD(O, i + 1 + hoff); SBAR();
;         mla_qkt_neg(p0, p1, negm, K0, qr, r32, hi);
;         if (i > 0) { pv_both_kp(o[0], o[1], vb0 + A_VBUF, pa0, pa1, pa2, pa3); }
;         HBAR();
;         __builtin_amdgcn_s_setprio(1);
;         SWRITE(E, i + hoff, kwE, vwE); SBAR();
;         mla_softmax_rel_kp(p0, p1, negm, first, l_reg, alpha, pa0, pa1, pa2, pa3); first = false; RESC(alpha);
;         __builtin_amdgcn_s_setprio(0);
;         HBAR();
;         SLOAD(E, i + 2 + hoff); SBAR();
;         mla_qkt_neg(p0, p1, negm, K1, qr, r32, hi);
;         pv_both_kp(o[0], o[1], vb0, pa0, pa1, pa2, pa3);
;         HBAR();
;         __builtin_amdgcn_s_setprio(1);
;         SWRITE(O, i + 1 + hoff, kwO, vwO); SBAR();
;         mla_softmax_rel_kp(p0, p1, negm, first, l_reg, alpha, pa0, pa1, pa2, pa3); first = false; RESC(alpha);
;         __builtin_amdgcn_s_setprio(0);
;         HBAR();
;     }
.LBB0_964:
	s_add_i32 s41, s41, 2
	s_add_u32 s60, s60, 0x20000
	s_addc_u32 s61, s61, 0
	s_add_u32 s62, s62, 0x20000
	s_addc_u32 s63, s63, 0
	s_cmp_lt_u32 s41, s54
	s_cbranch_scc0 .Lmla_exit_bar
	s_waitcnt lgkmcnt(0)
	s_cmp_eq_u32 s40, 0
	s_cbranch_scc0 .Lmla_nobar7
	s_barrier
.Lmla_nobar7:
	s_add_u32 s64, s64, 0x1000
	s_addc_u32 s65, s65, 0
	ds_read_b128 v[80:83], v157
	ds_read_b128 v[150:153], v157 offset:6656
	ds_read_b128 v[146:149], v157 offset:32
	ds_read_b128 v[168:171], v157 offset:6688
	v_cvt_pk_bf16_f32 v55, v245, v246
	v_cvt_pk_bf16_f32 v54, v243, v244
	v_cvt_pk_bf16_f32 v52, v234, v240
	v_cvt_pk_bf16_f32 v53, v241, v242
	v_cvt_pk_bf16_f32 v48, v247, v248
	v_cvt_pk_bf16_f32 v49, v249, v250
	v_cvt_pk_bf16_f32 v50, v251, v252
	v_cvt_pk_bf16_f32 v51, v253, v172
	v_cvt_pk_bf16_f32 v60, v218, v219
	v_cvt_pk_bf16_f32 v61, v220, v221
	v_cvt_pk_bf16_f32 v62, v222, v223
	v_cvt_pk_bf16_f32 v63, v224, v225
	v_cvt_pk_bf16_f32 v56, v226, v227
	v_cvt_pk_bf16_f32 v57, v228, v229
	v_cvt_pk_bf16_f32 v58, v230, v231
	v_cvt_pk_bf16_f32 v59, v232, v233
	s_branch .Lmla_s1e_body

; __device__ __forceinline__ void mla_softmax_rel_kp(f32x16& p0, f32x16& p1, f32x16& negm, bool first, float& l_reg, float& alpha, bf16x8& pa0, bf16x8& pa1, bf16x8& pa2, bf16x8& pa3) {
;     ...
;     if (__builtin_expect(first || !__all(pmax <= THR2), 0)) {
;         const float d = first ? pmax : fmaxf(pmax, 0.f);
;         if (!first) alpha = __builtin_amdgcn_exp2f(-d);
;         const float nm = negm[0] - d;
; #pragma unroll
;         for (int r = 0; r < 16; ++r) { negm[r] = nm; p0[r] -= d; p1[r] -= d; }
;     }
; #pragma unroll
;     for (int r = 0; r < 16; ++r) { p0[r] = __builtin_amdgcn_exp2f(p0[r]); p1[r] = __builtin_amdgcn_exp2f(p1[r]); }
;     float ps = 0.f;
; #pragma unroll
;     for (int r = 0; r < 16; ++r) ps += p0[r];
; #pragma unroll
;     for (int r = 0; r < 16; ++r) ps += p1[r];
;     { auto rr = __builtin_amdgcn_permlane32_swap(__float_as_uint(ps), __float_as_uint(ps), false, false); ps = __uint_as_float(rr[0]) + __uint_as_float(rr[1]); }
;     l_reg = l_reg * alpha + ps;
.LBB0_996:
	v_max3_f32 v81, v64, v65, v66
	v_max3_f32 v82, v67, v68, v69
	v_max3_f32 v83, v70, v71, v72
	v_max3_f32 v81, v81, v73, v74
	v_max3_f32 v82, v82, v75, v76
	v_max3_f32 v83, v83, v77, v78
	v_max3_f32 v81, v81, v79, v48
	v_max3_f32 v82, v82, v49, v50
	v_max3_f32 v83, v83, v51, v52
	v_max3_f32 v81, v81, v53, v54
	v_max3_f32 v82, v82, v55, v56
	v_max3_f32 v83, v83, v57, v58
	v_max3_f32 v81, v81, v59, v60
	v_max3_f32 v82, v82, v61, v62
	v_max3_f32 v81, v81, v82, v83
	v_max_f32_e32 v81, v81, v63
	v_mov_b32_e32 v82, v81
	s_nop 1
	v_permlane32_swap_b32_e32 v81, v82
	v_max_f32_e32 v81, v81, v82
	v_max_f32_e32 v33, v81, v81
	v_max_f32_e32 v34, 0, v33
	v_exp_f32_e64 v235, -v34
	v_sub_f32_e32 v32, v32, v34
	v_mul_f32_e32 v236, v236, v235
	v_mul_f32_e32 v237, v237, v235
	v_pk_add_f32 v[64:65], v[64:65], v[34:35] op_sel_hi:[1,0] neg_lo:[0,1] neg_hi:[0,1]
	v_pk_add_f32 v[48:49], v[48:49], v[34:35] op_sel_hi:[1,0] neg_lo:[0,1] neg_hi:[0,1]
	v_pk_add_f32 v[66:67], v[66:67], v[34:35] op_sel_hi:[1,0] neg_lo:[0,1] neg_hi:[0,1]
	v_pk_add_f32 v[50:51], v[50:51], v[34:35] op_sel_hi:[1,0] neg_lo:[0,1] neg_hi:[0,1]
	v_pk_add_f32 v[68:69], v[68:69], v[34:35] op_sel_hi:[1,0] neg_lo:[0,1] neg_hi:[0,1]
	v_pk_add_f32 v[52:53], v[52:53], v[34:35] op_sel_hi:[1,0] neg_lo:[0,1] neg_hi:[0,1]
	v_pk_add_f32 v[70:71], v[70:71], v[34:35] op_sel_hi:[1,0] neg_lo:[0,1] neg_hi:[0,1]
	v_pk_add_f32 v[54:55], v[54:55], v[34:35] op_sel_hi:[1,0] neg_lo:[0,1] neg_hi:[0,1]
	v_pk_add_f32 v[72:73], v[72:73], v[34:35] op_sel_hi:[1,0] neg_lo:[0,1] neg_hi:[0,1]
	v_pk_add_f32 v[56:57], v[56:57], v[34:35] op_sel_hi:[1,0] neg_lo:[0,1] neg_hi:[0,1]
	v_pk_add_f32 v[74:75], v[74:75], v[34:35] op_sel_hi:[1,0] neg_lo:[0,1] neg_hi:[0,1]
	v_pk_add_f32 v[58:59], v[58:59], v[34:35] op_sel_hi:[1,0] neg_lo:[0,1] neg_hi:[0,1]
	v_pk_add_f32 v[76:77], v[76:77], v[34:35] op_sel_hi:[1,0] neg_lo:[0,1] neg_hi:[0,1]
	v_pk_add_f32 v[60:61], v[60:61], v[34:35] op_sel_hi:[1,0] neg_lo:[0,1] neg_hi:[0,1]
	v_pk_add_f32 v[78:79], v[78:79], v[34:35] op_sel_hi:[1,0] neg_lo:[0,1] neg_hi:[0,1]
	v_pk_add_f32 v[62:63], v[62:63], v[34:35] op_sel_hi:[1,0] neg_lo:[0,1] neg_hi:[0,1]
	v_mov_b32_e32 v33, v32
	v_mov_b32_e32 v34, v32
	v_mov_b32_e32 v35, v32
	v_mov_b32_e32 v36, v32
	v_mov_b32_e32 v37, v32
	v_mov_b32_e32 v38, v32
	v_mov_b32_e32 v39, v32
	v_mov_b32_e32 v40, v32
	v_mov_b32_e32 v41, v32
	v_mov_b32_e32 v42, v32
	v_mov_b32_e32 v43, v32
	v_mov_b32_e32 v44, v32
	v_mov_b32_e32 v45, v32
	v_mov_b32_e32 v46, v32
	v_mov_b32_e32 v47, v32
	v_exp_f32_e32 v218, v64
	v_exp_f32_e32 v219, v65
	v_exp_f32_e32 v220, v66
	v_add_f32_e32 v236, v218, v236
	v_exp_f32_e32 v221, v67
	v_add_f32_e32 v236, v219, v236
	v_exp_f32_e32 v222, v68
	v_add_f32_e32 v236, v220, v236
	v_exp_f32_e32 v223, v69
	v_add_f32_e32 v236, v221, v236
	v_exp_f32_e32 v224, v70
	v_add_f32_e32 v236, v222, v236
	v_exp_f32_e32 v225, v71
	v_add_f32_e32 v236, v223, v236
	v_exp_f32_e32 v226, v72
	v_add_f32_e32 v236, v224, v236
	v_exp_f32_e32 v227, v73
	v_add_f32_e32 v236, v225, v236
	v_exp_f32_e32 v228, v74
	v_add_f32_e32 v236, v226, v236
	v_exp_f32_e32 v229, v75
	v_add_f32_e32 v236, v227, v236
	v_exp_f32_e32 v230, v76
	v_add_f32_e32 v236, v228, v236
	v_exp_f32_e32 v231, v77
	v_add_f32_e32 v236, v229, v236
	v_exp_f32_e32 v232, v78
	v_add_f32_e32 v236, v230, v236
	v_exp_f32_e32 v233, v79
	v_add_f32_e32 v236, v231, v236
	v_exp_f32_e32 v234, v48
	v_add_f32_e32 v236, v232, v236
	v_exp_f32_e32 v240, v49
	v_add_f32_e32 v236, v233, v236
	v_exp_f32_e32 v241, v50
	v_add_f32_e32 v236, v234, v236
	v_exp_f32_e32 v242, v51
	v_add_f32_e32 v236, v240, v236
	v_exp_f32_e32 v243, v52
	v_add_f32_e32 v236, v241, v236
	v_exp_f32_e32 v244, v53
	v_add_f32_e32 v236, v242, v236
	v_exp_f32_e32 v245, v54
	v_add_f32_e32 v236, v243, v236
	v_exp_f32_e32 v246, v55
	v_add_f32_e32 v236, v244, v236
	v_exp_f32_e32 v247, v56
	v_add_f32_e32 v236, v245, v236
	v_exp_f32_e32 v248, v57
	v_add_f32_e32 v236, v246, v236
	v_exp_f32_e32 v249, v58
	v_add_f32_e32 v236, v247, v236
	v_exp_f32_e32 v250, v59
	v_add_f32_e32 v236, v248, v236
	v_exp_f32_e32 v251, v60
	v_add_f32_e32 v236, v249, v236
	v_exp_f32_e32 v252, v61
	v_add_f32_e32 v236, v250, v236
	v_exp_f32_e32 v253, v62
	v_add_f32_e32 v236, v251, v236
	v_exp_f32_e32 v172, v63
	v_add_f32_e32 v236, v252, v236
	v_add_f32_e32 v236, v253, v236
	v_add_f32_e32 v236, v172, v236
	s_branch .Lmla_s2o_done
.Lmla_exit_bar:
	s_waitcnt lgkmcnt(0)
	s_cmp_eq_u32 s40, 0
	s_cbranch_scc0 .Lmla_exit_pack
	s_barrier
.Lmla_exit_pack:
	v_cvt_pk_bf16_f32 v55, v245, v246
	v_cvt_pk_bf16_f32 v54, v243, v244
	v_cvt_pk_bf16_f32 v52, v234, v240
	v_cvt_pk_bf16_f32 v53, v241, v242
	v_cvt_pk_bf16_f32 v48, v247, v248
	v_cvt_pk_bf16_f32 v49, v249, v250
	v_cvt_pk_bf16_f32 v50, v251, v252
	v_cvt_pk_bf16_f32 v51, v253, v172
	v_cvt_pk_bf16_f32 v60, v218, v219
	v_cvt_pk_bf16_f32 v61, v220, v221
	v_cvt_pk_bf16_f32 v62, v222, v223
	v_cvt_pk_bf16_f32 v63, v224, v225
	v_cvt_pk_bf16_f32 v56, v226, v227
	v_cvt_pk_bf16_f32 v57, v228, v229
	v_cvt_pk_bf16_f32 v58, v230, v231
	v_cvt_pk_bf16_f32 v59, v232, v233
